# scanstore: prompt scan tile output stage issues its four LDS reads together (four register groups) before the four global stores instead of a two-group read-wait-store ladder
# speedup vs baseline: 1.0079x; 1.0079x over previous
.LBB0_1017:
	v_pk_mul_f32 v[90:91], v[100:101], s[24:25] op_sel_hi:[1,0]
	v_pk_mul_f32 v[94:95], v[104:105], s[24:25] op_sel_hi:[1,0]
	v_pk_fma_f32 v[90:91], v[100:101], v[90:91], 1.0 op_sel_hi:[1,1,0]
	v_pk_mul_f32 v[96:97], v[102:103], s[24:25] op_sel_hi:[1,0]
	v_pk_mul_f32 v[92:93], v[98:99], s[24:25] op_sel_hi:[1,0]
	v_pk_mul_f32 v[90:91], v[100:101], v[90:91]
	v_pk_fma_f32 v[94:95], v[104:105], v[94:95], 1.0 op_sel_hi:[1,1,0]
	v_pk_fma_f32 v[96:97], v[102:103], v[96:97], 1.0 op_sel_hi:[1,1,0]
	v_pk_fma_f32 v[92:93], v[98:99], v[92:93], 1.0 op_sel_hi:[1,1,0]
	v_pk_mul_f32 v[94:95], v[104:105], v[94:95]
	v_pk_mul_f32 v[96:97], v[102:103], v[96:97]
	v_mul_f32_e32 v90, 0xc0135761, v90
	v_pk_mul_f32 v[92:93], v[98:99], v[92:93]
	v_mul_f32_e32 v96, 0xc0135761, v96
	v_exp_f32_e32 v106, v90
	v_mul_f32_e32 v90, 0xc0135761, v94
	v_mul_f32_e32 v92, 0xc0135761, v92
	v_exp_f32_e32 v96, v96
	v_mul_f32_e32 v93, 0xc0135761, v93
	v_exp_f32_e32 v107, v90
	v_mul_f32_e32 v90, 0xc0135761, v91
	v_exp_f32_e32 v92, v92
	v_exp_f32_e32 v93, v93
	v_mul_f32_e32 v97, 0xc0135761, v97
	v_exp_f32_e32 v108, v90
	v_mul_f32_e32 v90, 0xc0135761, v95
	v_exp_f32_e32 v97, v97
	v_exp_f32_e32 v109, v90
	v_add_f32_e32 v91, 1.0, v96
	v_add_f32_e32 v90, 1.0, v92
	v_rcp_f32_e32 v92, v91
	v_add_f32_e32 v91, 1.0, v93
	v_add_f32_e32 v95, 1.0, v107
	s_add_u32 s6, s26, s30
	v_rcp_f32_e32 v90, v90
	v_rcp_f32_e32 v91, v91
	v_add_f32_e32 v93, 1.0, v97
	v_add_f32_e32 v94, 1.0, v106
	v_rcp_f32_e32 v96, v95
	v_add_f32_e32 v95, 1.0, v108
	v_add_f32_e32 v97, 1.0, v109
	s_addc_u32 s7, s27, 0
	v_rcp_f32_e32 v94, v94
	v_rcp_f32_e32 v95, v95
	v_rcp_f32_e32 v97, v97
	v_rcp_f32_e32 v93, v93
	s_lshl_b64 s[6:7], s[6:7], 5
	s_add_u32 s6, s4, s6
	s_addc_u32 s7, s5, s7
	s_lshl_b32 s2, s2, 5
	v_pk_mul_f32 v[90:91], v[98:99], v[90:91]
	v_pk_mul_f32 v[94:95], v[100:101], v[94:95]
	v_pk_mul_f32 v[96:97], v[104:105], v[96:97]
	v_pk_mul_f32 v[92:93], v[102:103], v[92:93]
	v_cvt_pk_bf16_f32 v90, v90, v91
	v_cvt_pk_bf16_f32 v91, v94, v95
	v_add3_u32 v98, v214, s2, v210
	v_cvt_pk_bf16_f32 v92, v92, v93
	v_cvt_pk_bf16_f32 v93, v96, v97
	ds_write_b64 v98, v[90:91]
	ds_write_b64 v98, v[92:93] offset:8448
	v_pk_mul_f32 v[90:91], v[88:89], s[24:25] op_sel_hi:[1,0]
	v_pk_mul_f32 v[96:97], v[82:83], s[24:25] op_sel_hi:[1,0]
	v_pk_mul_f32 v[92:93], v[86:87], s[24:25] op_sel_hi:[1,0]
	v_pk_fma_f32 v[90:91], v[88:89], v[90:91], 1.0 op_sel_hi:[1,1,0]
	v_pk_mul_f32 v[94:95], v[84:85], s[24:25] op_sel_hi:[1,0]
	v_pk_fma_f32 v[96:97], v[82:83], v[96:97], 1.0 op_sel_hi:[1,1,0]
	v_pk_fma_f32 v[92:93], v[86:87], v[92:93], 1.0 op_sel_hi:[1,1,0]
	v_pk_mul_f32 v[90:91], v[88:89], v[90:91]
	v_pk_fma_f32 v[94:95], v[84:85], v[94:95], 1.0 op_sel_hi:[1,1,0]
	v_pk_mul_f32 v[96:97], v[82:83], v[96:97]
	v_pk_mul_f32 v[92:93], v[86:87], v[92:93]
	v_pk_mul_f32 v[94:95], v[84:85], v[94:95]
	v_mul_f32_e32 v96, 0xc0135761, v96
	v_mul_f32_e32 v90, 0xc0135761, v90
	v_mul_f32_e32 v92, 0xc0135761, v92
	v_exp_f32_e32 v96, v96
	v_mul_f32_e32 v93, 0xc0135761, v93
	v_exp_f32_e32 v99, v90
	v_mul_f32_e32 v90, 0xc0135761, v94
	v_exp_f32_e32 v92, v92
	v_exp_f32_e32 v93, v93
	v_mul_f32_e32 v97, 0xc0135761, v97
	v_exp_f32_e32 v100, v90
	v_mul_f32_e32 v90, 0xc0135761, v91
	v_exp_f32_e32 v97, v97
	v_exp_f32_e32 v101, v90
	v_mul_f32_e32 v90, 0xc0135761, v95
	v_exp_f32_e32 v102, v90
	v_add_f32_e32 v91, 1.0, v96
	v_add_f32_e32 v90, 1.0, v92
	v_rcp_f32_e32 v92, v91
	v_add_f32_e32 v91, 1.0, v93
	v_add_f32_e32 v95, 1.0, v100
	v_rcp_f32_e32 v90, v90
	v_rcp_f32_e32 v91, v91
	v_add_f32_e32 v93, 1.0, v97
	v_add_f32_e32 v94, 1.0, v99
	v_rcp_f32_e32 v96, v95
	v_add_f32_e32 v95, 1.0, v101
	v_rcp_f32_e32 v94, v94
	v_rcp_f32_e32 v95, v95
	v_add_f32_e32 v97, 1.0, v102
	v_rcp_f32_e32 v93, v93
	v_rcp_f32_e32 v97, v97
	v_pk_mul_f32 v[86:87], v[86:87], v[90:91]
	v_pk_mul_f32 v[88:89], v[88:89], v[94:95]
	v_pk_mul_f32 v[82:83], v[82:83], v[92:93]
	v_cvt_pk_bf16_f32 v86, v86, v87
	v_cvt_pk_bf16_f32 v87, v88, v89
	v_pk_mul_f32 v[84:85], v[84:85], v[96:97]
	v_cvt_pk_bf16_f32 v82, v82, v83
	v_lshl_add_u64 v[90:91], s[6:7], 0, v[168:169]
	v_cvt_pk_bf16_f32 v83, v84, v85
	ds_write_b64 v98, v[86:87] offset:16896
	ds_write_b64 v98, v[82:83] offset:25344
	s_waitcnt lgkmcnt(0)
	s_barrier
	v_add_u32_e32 v82, v215, v204
	ds_read_b128 v[82:85], v82
	v_add_u32_e32 v86, v215, v205
	ds_read_b128 v[86:89], v86
	v_add_u32_e32 v102, v215, v206
	ds_read_b128 v[102:105], v102
	v_add_u32_e32 v106, v215, v207
	ds_read_b128 v[106:109], v106
	v_add_co_u32_e32 v92, vcc, s12, v90
	v_addc_co_u32_e32 v93, vcc, 0, v91, vcc
	v_add_co_u32_e32 v94, vcc, 0x6000, v90
	v_addc_co_u32_e32 v95, vcc, 0, v91, vcc
	s_andn2_b64 vcc, exec, s[28:29]
	s_waitcnt lgkmcnt(3)
	global_store_dwordx4 v168, v[82:85], s[6:7]
	s_waitcnt lgkmcnt(2)
	global_store_dwordx4 v[92:93], v[86:89], off
	s_waitcnt lgkmcnt(1)
	global_store_dwordx4 v219, v[102:105], s[6:7]
	s_waitcnt lgkmcnt(0)
	global_store_dwordx4 v[94:95], v[106:109], off
	s_cbranch_vccnz .LBB0_1003
	s_mul_i32 s38, s38, 0x8400
	v_add_u32_e32 v82, s38, v167
	v_add_u32_e32 v83, v82, v207
	v_add_u32_e32 v84, v82, v206
	v_add_u32_e32 v85, v82, v205
	v_add_u32_e32 v82, v82, v204
	ds_write_b128 v82, v[66:69]
	ds_write_b128 v85, v[70:73]
	ds_write_b128 v84, v[74:77]
	ds_write_b128 v83, v[78:81]
	s_branch .LBB0_1003
